# mixer-A tile loop: last-tile no-DMA path moved out of line so the common path has no taken branch
# speedup vs baseline: 1.0059x; 1.0059x over previous
.LBB0_407:
	v_mbcnt_lo_u32_b32 v128, -1, 0
	v_mbcnt_hi_u32_b32 v128, -1, v128
	s_add_i32 s7, s7, 0
	v_bfe_u32 v129, v128, 2, 2
	v_lshrrev_b32_e32 v130, 3, v128
	v_bfe_u32 v132, v128, 1, 1
	v_and_or_b32 v131, v130, s64, v129
	v_and_or_b32 v130, v130, 2, v132
	v_lshlrev_b32_e32 v128, 3, v128
	v_lshlrev_b32_e32 v131, 8, v131
	v_lshlrev_b32_e32 v130, 4, v130
	v_and_b32_e32 v128, 8, v128
	v_or3_b32 v160, v130, v131, v128
	v_lshlrev_b32_e32 v162, 6, v129
	v_mbcnt_lo_u32_b32 v128, -1, 0
	v_mbcnt_hi_u32_b32 v128, -1, v128
	v_or_b32_e32 v163, v160, v162
	v_ashrrev_i32_e32 v129, 5, v128
	v_lshlrev_b32_e32 v130, 7, v128
	v_lshrrev_b32_e32 v133, 1, v128
	v_and_b32_e32 v132, 0xf80, v130
	v_bitop3_b32 v128, v133, v129, 7 bitop3:0x6c
	v_lshl_add_u32 v134, v128, 4, v132
	v_add_u32_e32 v128, 2, v129
	v_bitop3_b32 v128, v128, v133, 7 bitop3:0x78
	v_lshl_add_u32 v136, v128, 4, v132
	v_add_u32_e32 v128, 4, v129
	v_bitop3_b32 v128, v128, v133, 7 bitop3:0x78
	v_add_u32_e32 v207, s7, v134
	v_lshl_add_u32 v168, v128, 4, v132
	v_add_u32_e32 v135, 6, v129
	ds_read_b128 v[128:131], v207
	v_bitop3_b32 v133, v135, v133, 7 bitop3:0x78
	v_add_u32_e32 v224, s48, v134
	v_add_u32_e32 v225, s7, v136
	v_lshl_add_u32 v169, v133, 4, v132
	ds_read_b128 v[132:135], v224
	v_add_u32_e32 v226, s48, v136
	ds_read_b128 v[136:139], v225
	ds_read_b128 v[140:143], v226
	v_bitop3_b32 v203, v160, s37, v162 bitop3:0x36
	v_bitop3_b32 v206, v160, s41, v162 bitop3:0x36
	s_waitcnt lgkmcnt(2)
	v_mfma_f32_32x32x16_bf16 v[144:159], v[128:131], v[132:135], 0
	v_add_u32_e32 v227, s7, v168
	v_add_u32_e32 v228, s48, v168
	ds_read_b128 v[128:131], v227
	ds_read_b128 v[132:135], v228
	s_waitcnt lgkmcnt(2)
	v_mfma_f32_32x32x16_bf16 v[144:159], v[136:139], v[140:143], v[144:159]
	v_add_u32_e32 v230, s7, v169
	v_add_u32_e32 v232, s48, v169
	ds_read_b128 v[136:139], v230
	ds_read_b128 v[140:143], v232
	s_waitcnt lgkmcnt(2)
	v_mfma_f32_32x32x16_bf16 v[144:159], v[128:131], v[132:135], v[144:159]
	ds_read_b128 v[128:131], v207 offset:8192
	ds_read_b128 v[132:135], v224 offset:4096
	s_waitcnt lgkmcnt(2)
	v_mfma_f32_32x32x16_bf16 v[144:159], v[136:139], v[140:143], v[144:159]
	ds_read_b128 v[178:181], v225 offset:8192
	ds_read_b128 v[182:185], v226 offset:4096
	s_waitcnt lgkmcnt(2)
	v_mfma_f32_32x32x16_bf16 v[128:143], v[128:131], v[132:135], 0
	s_nop 7
	v_exp_f32_e32 v173, v144
	v_exp_f32_e32 v169, v145
	v_exp_f32_e32 v177, v146
	v_exp_f32_e32 v171, v147
	ds_read_b128 v[144:147], v227 offset:8192
	ds_read_b128 v[190:193], v228 offset:4096
	s_waitcnt lgkmcnt(2)
	v_mfma_f32_32x32x16_bf16 v[128:143], v[178:181], v[182:185], v[128:143]
	v_exp_f32_e32 v183, v148
	v_exp_f32_e32 v175, v149
	v_exp_f32_e32 v189, v150
	v_exp_f32_e32 v179, v151
	ds_read_b128 v[148:151], v230 offset:8192
	ds_read_b128 v[196:199], v232 offset:4096
	s_waitcnt lgkmcnt(2)
	v_mfma_f32_32x32x16_bf16 v[128:143], v[144:147], v[190:193], v[128:143]
	v_exp_f32_e32 v193, v152
	v_exp_f32_e32 v181, v153
	v_exp_f32_e32 v195, v154
	v_exp_f32_e32 v187, v155
	s_waitcnt lgkmcnt(0)
	v_mfma_f32_32x32x16_bf16 v[128:143], v[148:151], v[196:199], v[128:143]
	v_exp_f32_e32 v197, v156
	v_exp_f32_e32 v185, v157
	v_exp_f32_e32 v199, v158
	v_exp_f32_e32 v191, v159
	s_cmp_eq_u32 s4, 0x3f0000
	s_cbranch_scc1 .Lattn_nodma_a
	v_mov_b32_e32 v213, 0
	v_add_u32_e32 v212, s4, v202
	s_xor_b32 s8, s7, 0x4000
	v_lshl_add_u64 v[208:209], v[212:213], 1, s[66:67]
	s_add_i32 s9, s49, s8
	s_mov_b32 s10, m0
	s_mov_b32 m0, s9
	s_nop 0
	global_load_lds_dwordx4 v[208:209], off
	s_mov_b32 m0, s10
	v_add_u32_e32 v210, s4, v201
	v_lshl_add_u64 v[208:209], v[208:209], 0, s[38:39]
	s_add_i32 s9, s33, s8
	s_mov_b32 s10, m0
	s_mov_b32 m0, s9
	s_nop 0
	global_load_lds_dwordx4 v[208:209], off
	s_mov_b32 m0, s10
	v_add_u32_e32 v212, 0x10000, v210
	v_lshl_add_u64 v[208:209], v[212:213], 1, s[68:69]
	s_add_i32 s9, s54, s8
	s_mov_b32 s10, m0
	s_mov_b32 m0, s9
	s_nop 0
	global_load_lds_dwordx4 v[208:209], off
	s_mov_b32 m0, s10
	v_add_u32_e32 v212, 0x18000, v210
	v_lshl_add_u64 v[208:209], v[212:213], 1, s[68:69]
	s_add_i32 s8, s47, s8
	s_mov_b32 s9, m0
	s_mov_b32 m0, s8
	s_nop 0
	global_load_lds_dwordx4 v[208:209], off
	s_mov_b32 m0, s9
.Lattn_dma_done_a:
	v_exp_f32_e32 v172, v128
	v_exp_f32_e32 v170, v129
	v_exp_f32_e32 v176, v130
	v_exp_f32_e32 v168, v131
	v_exp_f32_e32 v182, v132
	v_exp_f32_e32 v178, v133
	v_exp_f32_e32 v188, v134
	v_exp_f32_e32 v174, v135
	v_exp_f32_e32 v192, v136
	v_exp_f32_e32 v186, v137
	v_exp_f32_e32 v194, v138
	v_exp_f32_e32 v180, v139
	v_exp_f32_e32 v196, v140
	v_exp_f32_e32 v190, v141
	v_exp_f32_e32 v198, v142
	v_exp_f32_e32 v184, v143
	v_cvt_pk_bf16_f32 v144, v173, v169
	v_cvt_pk_bf16_f32 v145, v177, v171
	v_cvt_pk_bf16_f32 v146, v183, v175
	v_cvt_pk_bf16_f32 v147, v189, v179
	v_cvt_pk_bf16_f32 v148, v193, v181
	v_cvt_pk_bf16_f32 v149, v195, v187
	v_cvt_pk_bf16_f32 v150, v197, v185
	v_cvt_pk_bf16_f32 v151, v199, v191
	v_cvt_pk_bf16_f32 v128, v172, v170
	v_cvt_pk_bf16_f32 v129, v176, v168
	v_cvt_pk_bf16_f32 v130, v182, v178
	v_cvt_pk_bf16_f32 v131, v188, v174
	v_cvt_pk_bf16_f32 v132, v192, v186
	v_cvt_pk_bf16_f32 v133, v194, v180
	v_cvt_pk_bf16_f32 v134, v196, v190
	v_cvt_pk_bf16_f32 v135, v198, v184
	v_add3_u32 v160, s7, v162, v160
	v_xad_u32 v252, v163, 64, s7
	v_add_u32_e32 v203, s7, v203
	v_add_u32_e32 v205, s7, v206
	ds_read_b64_tr_b16 v[136:137], v160 offset:32768
	ds_read_b64_tr_b16 v[138:139], v160 offset:34816
	ds_read_b64_tr_b16 v[140:141], v160 offset:36864
	ds_read_b64_tr_b16 v[142:143], v160 offset:38912
	ds_read_b64_tr_b16 v[152:153], v252 offset:32768
	ds_read_b64_tr_b16 v[154:155], v252 offset:34816
	ds_read_b64_tr_b16 v[156:157], v252 offset:36864
	ds_read_b64_tr_b16 v[158:159], v252 offset:38912
	ds_read_b64_tr_b16 v[208:209], v203 offset:32768
	ds_read_b64_tr_b16 v[210:211], v203 offset:34816
	ds_read_b64_tr_b16 v[212:213], v203 offset:36864
	ds_read_b64_tr_b16 v[214:215], v203 offset:38912
	ds_read_b64_tr_b16 v[216:217], v205 offset:32768
	ds_read_b64_tr_b16 v[218:219], v205 offset:34816
	ds_read_b64_tr_b16 v[220:221], v205 offset:36864
	ds_read_b64_tr_b16 v[222:223], v205 offset:38912
	s_waitcnt lgkmcnt(14)
	v_mfma_f32_32x32x16_bf16 v[64:79], v[144:147], v[136:139], v[64:79]
	v_mfma_f32_32x32x16_bf16 v[0:15], v[128:131], v[136:139], v[0:15]
	s_waitcnt lgkmcnt(10)
	v_mfma_f32_32x32x16_bf16 v[80:95], v[144:147], v[152:155], v[80:95]
	v_mfma_f32_32x32x16_bf16 v[16:31], v[128:131], v[152:155], v[16:31]
	s_waitcnt lgkmcnt(6)
	v_mfma_f32_32x32x16_bf16 v[96:111], v[144:147], v[208:211], v[96:111]
	v_mfma_f32_32x32x16_bf16 v[32:47], v[128:131], v[208:211], v[32:47]
	s_waitcnt lgkmcnt(2)
	v_mfma_f32_32x32x16_bf16 v[112:127], v[144:147], v[216:219], v[112:127]
	v_mfma_f32_32x32x16_bf16 v[48:63], v[128:131], v[216:219], v[48:63]
	v_mfma_f32_32x32x16_bf16 v[64:79], v[148:151], v[140:143], v[64:79]
	v_mfma_f32_32x32x16_bf16 v[0:15], v[132:135], v[140:143], v[0:15]
	v_mfma_f32_32x32x16_bf16 v[80:95], v[148:151], v[156:159], v[80:95]
	v_mfma_f32_32x32x16_bf16 v[16:31], v[132:135], v[156:159], v[16:31]
	v_mfma_f32_32x32x16_bf16 v[96:111], v[148:151], v[212:215], v[96:111]
	v_mfma_f32_32x32x16_bf16 v[32:47], v[132:135], v[212:215], v[32:47]
	s_waitcnt lgkmcnt(0)
	v_mfma_f32_32x32x16_bf16 v[112:127], v[148:151], v[220:223], v[112:127]
	v_mfma_f32_32x32x16_bf16 v[48:63], v[132:135], v[220:223], v[48:63]
	ds_read_b128 v[128:131], v207 offset:4096
	ds_read_b128 v[132:135], v224
	ds_read_b128 v[136:139], v225 offset:4096
	ds_read_b128 v[140:143], v226
	s_waitcnt lgkmcnt(2)
	v_mfma_f32_32x32x16_bf16 v[144:159], v[128:131], v[132:135], 0
	ds_read_b128 v[128:131], v227 offset:4096
	ds_read_b128 v[132:135], v228
	s_waitcnt lgkmcnt(2)
	v_mfma_f32_32x32x16_bf16 v[144:159], v[136:139], v[140:143], v[144:159]
	ds_read_b128 v[136:139], v230 offset:4096
	ds_read_b128 v[140:143], v232
	s_waitcnt lgkmcnt(2)
	v_mfma_f32_32x32x16_bf16 v[144:159], v[128:131], v[132:135], v[144:159]
	ds_read_b128 v[128:131], v207 offset:12288
	ds_read_b128 v[132:135], v224 offset:4096
	s_waitcnt lgkmcnt(2)
	v_mfma_f32_32x32x16_bf16 v[144:159], v[136:139], v[140:143], v[144:159]
	ds_read_b128 v[208:211], v225 offset:12288
	ds_read_b128 v[212:215], v226 offset:4096
	s_waitcnt lgkmcnt(2)
	v_mfma_f32_32x32x16_bf16 v[128:143], v[128:131], v[132:135], 0
	s_nop 7
	v_exp_f32_e32 v229, v144
	v_exp_f32_e32 v145, v145
	v_exp_f32_e32 v231, v146
	v_exp_f32_e32 v147, v147
	ds_read_b128 v[216:219], v227 offset:12288
	ds_read_b128 v[220:223], v228 offset:4096
	s_waitcnt lgkmcnt(2)
	v_mfma_f32_32x32x16_bf16 v[128:143], v[208:211], v[212:215], v[128:143]
	v_exp_f32_e32 v233, v148
	v_exp_f32_e32 v235, v149
	v_exp_f32_e32 v237, v150
	v_exp_f32_e32 v239, v151
	ds_read_b128 v[148:151], v230 offset:12288
	ds_read_b128 v[208:211], v232 offset:4096
	s_waitcnt lgkmcnt(2)
	v_mfma_f32_32x32x16_bf16 v[128:143], v[216:219], v[220:223], v[128:143]
	v_exp_f32_e32 v241, v152
	v_exp_f32_e32 v243, v153
	v_exp_f32_e32 v245, v154
	v_exp_f32_e32 v247, v155
	s_waitcnt lgkmcnt(0)
	v_mfma_f32_32x32x16_bf16 v[128:143], v[148:151], v[208:211], v[128:143]
	v_exp_f32_e32 v249, v156
	v_exp_f32_e32 v251, v157
	v_exp_f32_e32 v207, v158
	v_exp_f32_e32 v163, v159
	s_nop 7
	v_exp_f32_e32 v228, v128
	v_exp_f32_e32 v146, v129
	v_exp_f32_e32 v230, v130
	v_exp_f32_e32 v144, v131
	v_exp_f32_e32 v232, v132
	v_exp_f32_e32 v238, v133
	v_exp_f32_e32 v236, v134
	v_exp_f32_e32 v234, v135
	v_exp_f32_e32 v240, v136
	v_exp_f32_e32 v246, v137
	v_exp_f32_e32 v244, v138
	v_exp_f32_e32 v242, v139
	v_exp_f32_e32 v248, v140
	v_exp_f32_e32 v162, v141
	v_exp_f32_e32 v206, v142
	v_exp_f32_e32 v250, v143
	v_cvt_pk_bf16_f32 v148, v229, v145
	v_cvt_pk_bf16_f32 v149, v231, v147
	v_cvt_pk_bf16_f32 v150, v233, v235
	v_cvt_pk_bf16_f32 v151, v237, v239
	v_cvt_pk_bf16_f32 v152, v241, v243
	v_cvt_pk_bf16_f32 v153, v245, v247
	v_cvt_pk_bf16_f32 v154, v249, v251
	v_cvt_pk_bf16_f32 v155, v207, v163
	v_cvt_pk_bf16_f32 v128, v228, v146
	v_cvt_pk_bf16_f32 v129, v230, v144
	v_cvt_pk_bf16_f32 v130, v232, v238
	v_cvt_pk_bf16_f32 v131, v236, v234
	v_cvt_pk_bf16_f32 v132, v240, v246
	v_cvt_pk_bf16_f32 v133, v244, v242
	v_cvt_pk_bf16_f32 v134, v248, v162
	v_cvt_pk_bf16_f32 v135, v206, v250
	ds_read_b64_tr_b16 v[136:137], v160 offset:40960
	ds_read_b64_tr_b16 v[138:139], v160 offset:43008
	ds_read_b64_tr_b16 v[140:141], v160 offset:45056
	ds_read_b64_tr_b16 v[142:143], v160 offset:47104
	ds_read_b64_tr_b16 v[156:157], v252 offset:40960
	ds_read_b64_tr_b16 v[158:159], v252 offset:43008
	ds_read_b64_tr_b16 v[208:209], v252 offset:45056
	ds_read_b64_tr_b16 v[210:211], v252 offset:47104
	ds_read_b64_tr_b16 v[212:213], v203 offset:40960
	ds_read_b64_tr_b16 v[214:215], v203 offset:43008
	ds_read_b64_tr_b16 v[216:217], v203 offset:45056
	ds_read_b64_tr_b16 v[218:219], v203 offset:47104
	ds_read_b64_tr_b16 v[220:221], v205 offset:40960
	ds_read_b64_tr_b16 v[222:223], v205 offset:43008
	ds_read_b64_tr_b16 v[224:225], v205 offset:45056
	ds_read_b64_tr_b16 v[226:227], v205 offset:47104
	s_waitcnt lgkmcnt(14)
	v_mfma_f32_32x32x16_bf16 v[64:79], v[148:151], v[136:139], v[64:79]
	v_mfma_f32_32x32x16_bf16 v[0:15], v[128:131], v[136:139], v[0:15]
	s_waitcnt lgkmcnt(10)
	v_mfma_f32_32x32x16_bf16 v[80:95], v[148:151], v[156:159], v[80:95]
	v_mfma_f32_32x32x16_bf16 v[16:31], v[128:131], v[156:159], v[16:31]
	s_waitcnt lgkmcnt(6)
	v_mfma_f32_32x32x16_bf16 v[96:111], v[148:151], v[212:215], v[96:111]
	v_mfma_f32_32x32x16_bf16 v[32:47], v[128:131], v[212:215], v[32:47]
	s_waitcnt lgkmcnt(2)
	v_mfma_f32_32x32x16_bf16 v[112:127], v[148:151], v[220:223], v[112:127]
	v_mfma_f32_32x32x16_bf16 v[48:63], v[128:131], v[220:223], v[48:63]
	v_add_f32_e64 v128, v172, v176
	v_add_f32_e64 v129, v173, v177
	v_add_f32_e64 v130, v168, v170
	v_add_f32_e64 v131, v169, v171
	v_add_f32_e64 v128, v128, 0
	v_add_f32_e64 v129, v129, 0
	v_pk_add_f32 v[136:137], v[182:183], v[188:189]
	v_pk_add_f32 v[130:131], v[130:131], 0 op_sel_hi:[1,0]
	v_pk_add_f32 v[128:129], v[136:137], v[128:129]
	v_pk_add_f32 v[136:137], v[174:175], v[178:179]
	v_pk_add_f32 v[138:139], v[232:233], v[236:237]
	v_pk_add_f32 v[130:131], v[136:137], v[130:131]
	v_pk_add_f32 v[136:137], v[192:193], v[194:195]
	v_mfma_f32_32x32x16_bf16 v[64:79], v[152:155], v[140:143], v[64:79]
	v_add_f32_e64 v128, v136, v128
	v_add_f32_e64 v129, v137, v129
	v_add_f32_e64 v136, v180, v186
	v_add_f32_e64 v137, v181, v187
	v_add_f32_e64 v130, v136, v130
	v_add_f32_e64 v131, v137, v131
	v_pk_add_f32 v[136:137], v[196:197], v[198:199]
	s_nop 0
	v_pk_add_f32 v[128:129], v[136:137], v[128:129]
	v_pk_add_f32 v[136:137], v[184:185], v[190:191]
	v_mfma_f32_32x32x16_bf16 v[0:15], v[132:135], v[140:143], v[0:15]
	v_add_f32_e64 v130, v136, v130
	v_add_f32_e64 v131, v137, v131
	v_add_f32_e64 v136, v144, v146
	v_add_f32_e64 v137, v145, v147
	v_add_f32_e64 v128, v128, v130
	v_add_f32_e64 v129, v129, v131
	v_pk_add_f32 v[130:131], v[228:229], v[230:231]
	v_pk_add_f32 v[136:137], v[136:137], 0 op_sel_hi:[1,0]
	v_pk_add_f32 v[130:131], v[130:131], 0 op_sel_hi:[1,0]
	v_pk_add_f32 v[128:129], v[166:167], v[128:129]
	v_mfma_f32_32x32x16_bf16 v[80:95], v[152:155], v[208:211], v[80:95]
	v_add_f32_e64 v130, v138, v130
	v_add_f32_e64 v131, v139, v131
	v_add_f32_e64 v138, v234, v238
	v_add_f32_e64 v139, v235, v239
	v_add_f32_e64 v136, v138, v136
	v_add_f32_e64 v137, v139, v137
	v_pk_add_f32 v[138:139], v[240:241], v[244:245]
	s_nop 0
	v_pk_add_f32 v[130:131], v[138:139], v[130:131]
	v_mfma_f32_32x32x16_bf16 v[16:31], v[132:135], v[208:211], v[16:31]
	v_add_f32_e64 v138, v242, v246
	v_add_f32_e64 v139, v243, v247
	v_add_f32_e64 v136, v138, v136
	v_add_f32_e64 v137, v139, v137
	v_add_f32_e64 v138, v248, v206
	v_add_f32_e64 v139, v249, v207
	v_pk_add_f32 v[130:131], v[138:139], v[130:131]
	v_pk_add_f32 v[138:139], v[250:251], v[162:163]
	v_mfma_f32_32x32x16_bf16 v[96:111], v[152:155], v[216:219], v[96:111]
	v_add_f32_e64 v136, v138, v136
	v_add_f32_e64 v137, v139, v137
	v_add_f32_e64 v130, v130, v136
	v_add_f32_e64 v131, v131, v137
	v_add_f32_e64 v166, v128, v130
	v_add_f32_e64 v167, v129, v131
	v_mfma_f32_32x32x16_bf16 v[32:47], v[132:135], v[216:219], v[32:47]
	s_waitcnt lgkmcnt(0)
	v_mfma_f32_32x32x16_bf16 v[112:127], v[152:155], v[224:227], v[112:127]
	v_mfma_f32_32x32x16_bf16 v[48:63], v[132:135], v[224:227], v[48:63]
	s_waitcnt vmcnt(0)
	s_waitcnt lgkmcnt(0)
	s_addk_i32 s5, 0x4000
	s_add_i32 s4, s4, 0x10000
	s_cmp_eq_u32 s4, 0x400000
	s_barrier
	s_cbranch_scc1 .LBB0_410

.Lattn_nodma_a:
	s_nop 7
	s_branch .Lattn_dma_done_a
